# the 64 gMLP roles of the mixer phase go to the workgroups whose mixer-in tile was a q tile (cheapest epilogue): they reach the mixer-in barrier first and, not waiting for its release, start the mixer'
# speedup vs baseline: 1.0118x; 1.0036x over previous
.LBB0_939:
	s_or_b64 exec, exec, s[12:13]
	v_cvt_f32_u32_e32 v4, v2
	s_waitcnt vmcnt(0)
	v_readfirstlane_b32 s2, v3
	v_sub_u32_e32 v3, 0, v2
	v_rcp_iflag_f32_e32 v4, v4
	v_add_u32_e32 v5, s2, v1
	v_mul_f32_e32 v4, 0x4f7ffffe, v4
	v_cvt_u32_f32_e32 v4, v4
	v_mul_lo_u32 v1, v3, v4
	v_mul_hi_u32 v1, v4, v1
	v_add_u32_e32 v1, v4, v1
	v_mul_hi_u32 v1, v5, v1
	v_mul_lo_u32 v3, v1, v2
	v_sub_u32_e32 v3, v5, v3
	v_add_u32_e32 v4, 1, v1
	v_cmp_ge_u32_e32 vcc, v3, v2
	s_nop 1
	v_cndmask_b32_e32 v1, v1, v4, vcc
	v_sub_u32_e32 v4, v3, v2
	v_cndmask_b32_e32 v3, v3, v4, vcc
	v_add_u32_e32 v4, 1, v1
	v_cmp_ge_u32_e32 vcc, v3, v2
	v_add_u32_e32 v3, 1, v5
	s_nop 0
	v_cndmask_b32_e32 v1, v1, v4, vcc
	v_mul_lo_u32 v4, v2, v1
	v_add_u32_e32 v2, v4, v2
	v_cmp_ne_u32_e32 vcc, v3, v2
	s_and_saveexec_b64 s[10:11], vcc
	s_xor_b64 s[10:11], exec, s[10:11]
	s_cbranch_execz .LBB0_953
	v_readlane_b32 s18, v255, 0
	s_nop 0
	s_cmp_lt_u32 s18, 0x80
	s_cbranch_scc0 .Lb5_std
	s_bitcmp0_b32 s18, 0
	s_cbranch_scc0 .Lb5_std
	s_lshr_b32 s18, s18, 1
	s_and_b32 s18, s18, 31
	s_lshl_b32 s18, s18, 7
	s_add_u32 s18, s18, 0xb000
	v_readlane_b32 s19, v255, 47
	v_mov_b32_e32 v0, s18
	s_mov_b32 s2, 0
	s_waitcnt lgkmcnt(0)

.LBB0_973:
	s_or_b64 exec, exec, s[4:5]
	s_waitcnt lgkmcnt(0)
	s_barrier
	s_load_dwordx2 s[4:5], s[16:17], 0x98
	v_readlane_b32 s2, v255, 0
	s_nop 0
	s_cmp_ge_u32 s2, 0x80
	s_cbranch_scc1 .Lvbx_done
	s_and_b32 s6, s2, 1
	s_lshl_b32 s6, s6, 6
	s_lshr_b32 s2, s2, 1
	s_or_b32 s2, s2, s6
.Lvbx_done:
	v_mov_b32_e32 v166, v147
	s_cmp_gt_i32 s2, 63
	v_readfirstlane_b32 s20, v166
	s_mov_b64 s[6:7], -1
	s_cbranch_scc0 .LBB0_992
	s_cmpk_gt_u32 s2, 0x5f
	s_mov_b64 s[56:57], s[16:17]
	s_cbranch_scc1 .LBB0_991
	v_mov_b32_e32 v11, v147
	s_sub_i32 s6, s2, 64
	s_cmp_gt_u32 s6, 15
	v_readfirstlane_b32 s18, v11
	s_cbranch_scc1 .LBB0_983
	v_lshlrev_b32_e32 v0, 4, v11
	v_add_u32_e32 v1, 0x2000, v0
	v_ashrrev_i32_e32 v2, 31, v1
	v_lshrrev_b32_e32 v2, 22, v2
	v_add_u32_e32 v2, v1, v2
	v_ashrrev_i32_e32 v8, 10, v2
	v_mul_i32_i24_e32 v2, 0x400, v8
	v_sub_u32_e32 v1, v1, v2
	v_lshrrev_b32_e32 v2, 4, v1
	v_bitop3_b32 v1, v2, v1, 32 bitop3:0x6c
	v_ashrrev_i32_e32 v2, 31, v1
	v_lshrrev_b32_e32 v2, 26, v2
	v_add_u32_e32 v2, v1, v2
	v_lshlrev_b32_e32 v3, 3, v8
	v_ashrrev_i32_e32 v9, 6, v2
	v_and_b32_e32 v3, -16, v3
	v_add_u32_e32 v3, v9, v3
	v_and_b32_e32 v4, 3, v9
	s_mov_b32 s7, 0xfffe0
	v_lshrrev_b32_e32 v5, 2, v3
	v_lshlrev_b32_e32 v6, 1, v3
	v_and_b32_e32 v2, 0xc0, v2
	v_and_or_b32 v4, v3, s7, v4
	v_and_b32_e32 v5, 4, v5
	v_and_b32_e32 v6, 24, v6
	v_sub_u32_e32 v1, v1, v2
	v_or3_b32 v4, v4, v5, v6
	v_lshlrev_b32_e32 v5, 5, v8
	v_ashrrev_i16_sdwa v1, v189, sext(v1) dst_sel:DWORD dst_unused:UNUSED_PAD src0_sel:DWORD src1_sel:BYTE_0
	v_and_b32_e32 v5, 32, v5
	v_bfe_i32 v10, v1, 0, 16
	v_add_lshl_u32 v1, v5, v10, 1
	v_lshl_add_u32 v130, v4, 12, v1
	v_lshl_add_u32 v132, v3, 12, v1
	v_bfe_i32 v1, v11, 27, 1
	v_lshrrev_b32_e32 v1, 22, v1
	v_add_u32_e32 v1, v0, v1
	v_and_b32_e32 v1, 0xfffffc00, v1
	v_sub_u32_e32 v0, v0, v1
	v_lshrrev_b32_e32 v1, 4, v0
	v_bitop3_b32 v1, v1, v0, 32 bitop3:0x6c
	v_ashrrev_i32_e32 v0, 31, v0
	v_lshrrev_b32_e32 v0, 26, v0
	v_add_u32_e32 v0, v1, v0
	v_ashrrev_i32_e32 v12, 6, v0
	v_ashrrev_i32_e32 v0, 31, v11
	v_lshrrev_b32_e32 v0, 26, v0
	v_add_u32_e32 v0, v11, v0
	v_ashrrev_i32_e32 v13, 6, v0
	v_lshlrev_b32_e32 v0, 3, v13
	v_and_b32_e32 v0, -16, v0
	v_add_u32_e32 v0, v12, v0
	v_and_b32_e32 v2, 3, v12
	v_lshrrev_b32_e32 v3, 2, v0
	v_lshlrev_b32_e32 v4, 1, v0
	s_ashr_i32 s10, s18, 6
	v_and_or_b32 v2, v0, s7, v2
	v_and_b32_e32 v3, 4, v3
	v_and_b32_e32 v4, 24, v4
	s_and_b32 s21, s2, 3
	s_lshr_b32 s22, s6, 2
	s_ashr_i32 s11, s18, 8
	s_lshl_b32 s19, s10, 10
	v_or3_b32 v2, v2, v3, v4
	v_mul_i32_i24_e32 v4, 64, v12
	s_lshl_b32 s13, s21, 20
	s_lshl_b32 s12, s22, 20
	v_sub_u32_e32 v1, v1, v4
	s_waitcnt lgkmcnt(0)
	s_add_u32 s8, s4, s12
	v_lshlrev_b32_e32 v3, 5, v13
	v_ashrrev_i16_sdwa v1, v189, sext(v1) dst_sel:DWORD dst_unused:UNUSED_PAD src0_sel:DWORD src1_sel:BYTE_0
	s_addc_u32 s9, s5, 0
	v_and_b32_e32 v3, 32, v3
	v_bfe_i32 v14, v1, 0, 16
	s_add_u32 s6, s8, 0x3c00000
	v_add_lshl_u32 v1, v3, v14, 1
	s_addc_u32 s7, s9, 0
	s_add_i32 s23, s19, 0
	v_lshl_add_u32 v144, v2, 12, v1
	s_add_i32 m0, s23, 0x10000
	v_lshl_add_u32 v134, v0, 12, v1
	global_load_lds_dwordx4 v144, s[6:7]
	s_add_i32 m0, s23, 0x12000
	s_add_u32 s8, s8, 0x3c80000
	global_load_lds_dwordx4 v130, s[6:7]
	s_addc_u32 s9, s9, 0
	s_add_i32 m0, s23, 0x14000
	v_mov_b32_e32 v131, v145
	global_load_lds_dwordx4 v144, s[8:9]
	s_add_i32 m0, s23, 0x16000
	s_add_u32 s14, s4, s13
	s_addc_u32 s15, s5, 0
	global_load_lds_dwordx4 v130, s[8:9]
	s_add_u32 s8, s14, 0x200000
	s_addc_u32 s9, s15, 0
	s_add_i32 s24, s23, 0x2000
	s_mov_b32 m0, s23
	s_add_u32 s14, s14, 0x280000
	global_load_lds_dwordx4 v134, s[8:9]
	s_mov_b32 m0, s24
	s_addc_u32 s15, s15, 0
	s_add_i32 s25, s23, 0x4000
	global_load_lds_dwordx4 v132, s[8:9]
	s_mov_b32 m0, s25
	s_add_i32 s26, s23, 0x6000
	global_load_lds_dwordx4 v134, s[14:15]
	s_mov_b32 m0, s26
	v_mov_b32_e32 v135, v145
	global_load_lds_dwordx4 v132, s[14:15]
	v_mov_b32_e32 v133, v145
	v_lshl_add_u64 v[6:7], s[6:7], 0, v[144:145]
	v_lshl_add_u64 v[4:5], s[6:7], 0, v[130:131]
	v_lshl_add_u64 v[2:3], s[8:9], 0, v[134:135]
	s_cmp_lg_u32 s11, 1
	v_lshl_add_u64 v[0:1], s[8:9], 0, v[132:133]
	s_cbranch_scc1 .LBB0_978
	s_barrier
